# banded attention tile loop: K fragments of QK read 3 pairs ahead in a 4-buffer register ring, first V fragment group read during the exps
# baseline (speedup 1.0000x reference)
; __device__ __forceinline__ void partialSM(f32x16& p0, f32x16& p1, float& m_reg, float& mn, float& alpha) {
;     ...
;   float mnC = -mn * C;
; #pragma unroll
;   for (int r = 0; r < 16; ++r) p0[r] = fmaf(p0[r], C, mnC);
; #pragma unroll
;   for (int r = 0; r < 16; ++r) p1[r] = fmaf(p1[r], C, mnC);
; #pragma unroll
;   for (int r = 0; r < 16; ++r) p0[r] = __builtin_amdgcn_exp2f(p0[r]);
; }
; __device__ __forceinline__ void finishSM(f32x16& p0, f32x16& p1, float alpha, float& l_reg, bf16x8& pa0, bf16x8& pa1, bf16x8& pa2, bf16x8& pa3) {
; #pragma unroll
;   for (int r = 0; r < 16; ++r) p1[r] = __builtin_amdgcn_exp2f(p1[r]);
;   float ps = 0;
; #pragma unroll
;   for (int r = 0; r < 16; ++r) ps += p0[r];
; #pragma unroll
;   for (int r = 0; r < 16; ++r) ps += p1[r];
;   { auto rr = __builtin_amdgcn_permlane32_swap(__float_as_uint(ps), __float_as_uint(ps), false, false);
;     ps = __uint_as_float(rr[0]) + __uint_as_float(rr[1]); }
;   l_reg = l_reg * alpha + ps;
;     ...
;   PK4(p0, 0, pa0); PK4(p0, 8, pa1); PK4(p1, 0, pa2); PK4(p1, 8, pa3);
;     ...
; }
; __device__ __forceinline__ void qkt(f32x16& p0, f32x16& p1, const bf16* Ks, const bf16x8* qr, int r32, int hi) {
;   p0 = f32x16{}; p1 = f32x16{};
; #pragma unroll
;   for (int d0 = 0; d0 < 8; ++d0) { int cb = (d0 * 16 + hi * 8) * 2;
;     bf16x8 b0 = *reinterpret_cast<const bf16x8*>((const char*)Ks + KSWZ(r32, cb));
;     bf16x8 b1 = *reinterpret_cast<const bf16x8*>((const char*)Ks + KSWZ(32 + r32, cb));
;     p0 = __builtin_amdgcn_mfma_f32_32x32x16_bf16(b0, qr[d0], p0, 0, 0, 0);
;     p1 = __builtin_amdgcn_mfma_f32_32x32x16_bf16(b1, qr[d0], p1, 0, 0, 0); }
; }
; __device__ __forceinline__ int v_st(int k, int c) { const int kk = (k & ~0xC) | ((k & 4) << 1) | ((k & 8) >> 1); return ((kk >> 3) * 4 + (c >> 5)) * 512 + ((kk & 7) * 32 + (c & 31)) * 2; }
; __device__ __forceinline__ int v_rd_base(int lane) { return ((lane & 3) << 3) | (((lane >> 2) & 3) << 6) | (((lane >> 4) & 1) << 5) | (((lane >> 5) & 1) << 8); }
; template <int OFF> __device__ __forceinline__ s16x4 tr_read(int vb) {
;   s16x4 r; asm volatile("ds_read_b64_tr_b16 %0, %1 offset:%2" : "=&v"(r) : "v"(vb), "i"(OFF) : "memory"); return r;
; }
; template <int D0> __device__ __forceinline__ void pv_one(f32x16& od, int vb, bf16x8 pa0, bf16x8 pa1, bf16x8 pa2, bf16x8 pa3) {
.LBB0_514:
	v_cndmask_b32_e64 v201, v65, v201, s[4:5]
	v_mul_f32_e32 v65, 0xbe0293ee, v201
	v_fmamk_f32 v66, v176, 0x3e0293ee, v65
	v_fmamk_f32 v67, v177, 0x3e0293ee, v65
	v_exp_f32_e32 v66, v66
	v_fmamk_f32 v68, v178, 0x3e0293ee, v65
	v_exp_f32_e32 v67, v67
	v_fmamk_f32 v69, v179, 0x3e0293ee, v65
	v_exp_f32_e32 v68, v68
	v_fmamk_f32 v70, v182, 0x3e0293ee, v65
	v_fmamk_f32 v71, v183, 0x3e0293ee, v65
	v_fmamk_f32 v72, v180, 0x3e0293ee, v65
	v_fmamk_f32 v73, v181, 0x3e0293ee, v65
	v_fmamk_f32 v74, v172, 0x3e0293ee, v65
	v_fmamk_f32 v75, v173, 0x3e0293ee, v65
	v_fmamk_f32 v76, v174, 0x3e0293ee, v65
	v_fmamk_f32 v77, v175, 0x3e0293ee, v65
	v_fmamk_f32 v78, v170, 0x3e0293ee, v65
	v_fmamk_f32 v79, v171, 0x3e0293ee, v65
	v_fmamk_f32 v80, v168, 0x3e0293ee, v65
	v_fmamk_f32 v81, v169, 0x3e0293ee, v65
	v_fmamk_f32 v82, v196, 0x3e0293ee, v65
	v_fmamk_f32 v83, v197, 0x3e0293ee, v65
	v_fmamk_f32 v84, v198, 0x3e0293ee, v65
	v_fmamk_f32 v85, v199, 0x3e0293ee, v65
	v_fmamk_f32 v86, v194, 0x3e0293ee, v65
	v_fmamk_f32 v87, v195, 0x3e0293ee, v65
	v_fmamk_f32 v88, v190, 0x3e0293ee, v65
	v_fmamk_f32 v89, v191, 0x3e0293ee, v65
	v_fmamk_f32 v90, v192, 0x3e0293ee, v65
	v_fmamk_f32 v91, v193, 0x3e0293ee, v65
	v_fmamk_f32 v92, v188, 0x3e0293ee, v65
	v_fmamk_f32 v93, v189, 0x3e0293ee, v65
	v_fmamk_f32 v94, v186, 0x3e0293ee, v65
	v_fmamk_f32 v95, v187, 0x3e0293ee, v65
	v_fmamk_f32 v168, v184, 0x3e0293ee, v65
	v_fmac_f32_e32 v65, 0x3e0293ee, v185
	ds_read_b64_tr_b16 v[176:177], v204 offset:0
	ds_read_b64_tr_b16 v[178:179], v204 offset:0x800
	ds_read_b64_tr_b16 v[180:181], v204 offset:0x1000
	ds_read_b64_tr_b16 v[182:183], v204 offset:0x1800
	ds_read_b64_tr_b16 v[184:185], v204 offset:0x2000
	ds_read_b64_tr_b16 v[186:187], v204 offset:0x2800
	ds_read_b64_tr_b16 v[188:189], v204 offset:0x3000
	ds_read_b64_tr_b16 v[190:191], v204 offset:0x3800
	v_exp_f32_e32 v69, v69
	v_exp_f32_e32 v70, v70
	v_exp_f32_e32 v169, v65
	v_add_f32_e32 v65, 0, v66
	v_exp_f32_e32 v71, v71
	v_add_f32_e32 v65, v67, v65
	v_exp_f32_e32 v72, v72
	v_add_f32_e32 v65, v68, v65
	v_exp_f32_e32 v73, v73
	v_add_f32_e32 v65, v69, v65
	v_exp_f32_e32 v74, v74
	v_add_f32_e32 v65, v70, v65
	v_exp_f32_e32 v75, v75
	v_add_f32_e32 v65, v71, v65
	v_exp_f32_e32 v76, v76
	v_add_f32_e32 v65, v72, v65
	v_exp_f32_e32 v77, v77
	v_add_f32_e32 v65, v73, v65
	v_exp_f32_e32 v78, v78
	v_add_f32_e32 v65, v74, v65
	v_exp_f32_e32 v79, v79
	v_add_f32_e32 v65, v75, v65
	v_exp_f32_e32 v80, v80
	v_add_f32_e32 v65, v76, v65
	v_exp_f32_e32 v81, v81
	v_add_f32_e32 v65, v77, v65
	v_exp_f32_e32 v82, v82
	v_add_f32_e32 v65, v78, v65
	v_exp_f32_e32 v83, v83
	v_add_f32_e32 v65, v79, v65
	v_exp_f32_e32 v84, v84
	v_add_f32_e32 v65, v80, v65
	v_exp_f32_e32 v85, v85
	v_add_f32_e32 v65, v81, v65
	v_exp_f32_e32 v86, v86
	v_add_f32_e32 v65, v82, v65
	v_exp_f32_e32 v87, v87
	v_add_f32_e32 v65, v83, v65
	v_exp_f32_e32 v88, v88
	v_add_f32_e32 v65, v84, v65
	v_exp_f32_e32 v89, v89
	v_add_f32_e32 v65, v85, v65
	v_exp_f32_e32 v90, v90
	v_add_f32_e32 v65, v86, v65
	v_exp_f32_e32 v91, v91
	v_add_f32_e32 v65, v87, v65
	v_exp_f32_e32 v92, v92
	v_add_f32_e32 v65, v88, v65
	v_exp_f32_e32 v93, v93
	v_add_f32_e32 v65, v89, v65
	v_exp_f32_e32 v94, v94
	v_add_f32_e32 v65, v90, v65
	v_exp_f32_e32 v95, v95
	v_add_f32_e32 v65, v91, v65
	v_exp_f32_e32 v168, v168
	v_add_f32_e32 v65, v92, v65
	v_add_f32_e32 v65, v93, v65
	v_add_f32_e32 v65, v94, v65
	v_add_f32_e32 v65, v95, v65
	v_add_f32_e32 v65, v168, v65
	v_add_f32_e32 v65, v169, v65
	v_mov_b32_e32 v170, v65
	s_nop 1
	v_permlane32_swap_b32_e32 v65, v170
	v_add_f32_e32 v170, v65, v170
	v_fmac_f32_e32 v170, v216, v64
	v_cvt_pk_bf16_f32 v64, v66, v67
	v_cvt_pk_bf16_f32 v65, v68, v69
	v_cvt_pk_bf16_f32 v66, v70, v71
	v_cvt_pk_bf16_f32 v67, v72, v73
	v_cvt_pk_bf16_f32 v68, v74, v75
	v_cvt_pk_bf16_f32 v69, v76, v77
	v_cvt_pk_bf16_f32 v70, v78, v79
	v_cvt_pk_bf16_f32 v71, v80, v81
	v_cvt_pk_bf16_f32 v72, v82, v83
	v_cvt_pk_bf16_f32 v73, v84, v85
	v_cvt_pk_bf16_f32 v74, v86, v87
	v_cvt_pk_bf16_f32 v75, v88, v89
	v_cvt_pk_bf16_f32 v76, v90, v91
	v_cvt_pk_bf16_f32 v77, v92, v93
	v_cvt_pk_bf16_f32 v78, v94, v95
	v_cvt_pk_bf16_f32 v79, v168, v169
	s_nop 0
	v_permlane32_swap_b32_e32 v64, v66
	v_permlane32_swap_b32_e32 v65, v67
	v_permlane32_swap_b32_e32 v68, v70
	v_permlane32_swap_b32_e32 v69, v71
	v_permlane32_swap_b32_e32 v72, v74
	v_permlane32_swap_b32_e32 v73, v75
	v_permlane32_swap_b32_e32 v76, v78
	v_permlane32_swap_b32_e32 v77, v79
	s_waitcnt lgkmcnt(0)
	s_nop 0
	v_mfma_f32_32x32x16_bf16 v[0:15], v[64:67], v[176:179], v[0:15]
	ds_read_b64_tr_b16 v[80:81], v204 offset:0x200
	ds_read_b64_tr_b16 v[82:83], v204 offset:0xa00
	v_mfma_f32_32x32x16_bf16 v[0:15], v[68:71], v[180:183], v[0:15]
	ds_read_b64_tr_b16 v[84:85], v204 offset:0x1200
	ds_read_b64_tr_b16 v[86:87], v204 offset:0x1a00
	v_mfma_f32_32x32x16_bf16 v[0:15], v[72:75], v[184:187], v[0:15]
	ds_read_b64_tr_b16 v[88:89], v204 offset:0x2200
	ds_read_b64_tr_b16 v[90:91], v204 offset:0x2a00
	v_mfma_f32_32x32x16_bf16 v[0:15], v[76:79], v[188:191], v[0:15]
	ds_read_b64_tr_b16 v[92:93], v204 offset:0x3200
	ds_read_b64_tr_b16 v[94:95], v204 offset:0x3a00
	s_waitcnt lgkmcnt(0)
	v_mfma_f32_32x32x16_bf16 v[48:63], v[64:67], v[80:83], v[48:63]
	ds_read_b64_tr_b16 v[80:81], v204 offset:0x400
	ds_read_b64_tr_b16 v[82:83], v204 offset:0xc00
	v_mfma_f32_32x32x16_bf16 v[48:63], v[68:71], v[84:87], v[48:63]
	ds_read_b64_tr_b16 v[84:85], v204 offset:0x1400
	ds_read_b64_tr_b16 v[86:87], v204 offset:0x1c00
	v_mfma_f32_32x32x16_bf16 v[48:63], v[72:75], v[88:91], v[48:63]
	ds_read_b64_tr_b16 v[88:89], v204 offset:0x2400
	ds_read_b64_tr_b16 v[90:91], v204 offset:0x2c00
	v_mfma_f32_32x32x16_bf16 v[48:63], v[76:79], v[92:95], v[48:63]
	ds_read_b64_tr_b16 v[92:93], v204 offset:0x3400
	ds_read_b64_tr_b16 v[94:95], v204 offset:0x3c00
	s_waitcnt lgkmcnt(0)
	v_mfma_f32_32x32x16_bf16 v[32:47], v[64:67], v[80:83], v[32:47]
	ds_read_b64_tr_b16 v[80:81], v204 offset:0x600
	ds_read_b64_tr_b16 v[82:83], v204 offset:0xe00
	v_mfma_f32_32x32x16_bf16 v[32:47], v[68:71], v[84:87], v[32:47]
	ds_read_b64_tr_b16 v[84:85], v204 offset:0x1600
	ds_read_b64_tr_b16 v[86:87], v204 offset:0x1e00
	v_mfma_f32_32x32x16_bf16 v[32:47], v[72:75], v[88:91], v[32:47]
	ds_read_b64_tr_b16 v[88:89], v204 offset:0x2600
	ds_read_b64_tr_b16 v[90:91], v204 offset:0x2e00
	v_mfma_f32_32x32x16_bf16 v[32:47], v[76:79], v[92:95], v[32:47]
	ds_read_b64_tr_b16 v[92:93], v204 offset:0x3600
	ds_read_b64_tr_b16 v[94:95], v204 offset:0x3e00
	s_waitcnt lgkmcnt(0)
	v_mfma_f32_32x32x16_bf16 v[16:31], v[64:67], v[80:83], v[16:31]
	v_mov_b32_e32 v216, v170
	v_mfma_f32_32x32x16_bf16 v[16:31], v[68:71], v[84:87], v[16:31]
	v_mfma_f32_32x32x16_bf16 v[16:31], v[72:75], v[88:91], v[16:31]
	v_mfma_f32_32x32x16_bf16 v[16:31], v[76:79], v[92:95], v[16:31]

; __device__ __forceinline__ void qkt(f32x16& p0, f32x16& p1, const bf16* Ks, const bf16x8* qr, int r32, int hi) {
;   p0 = f32x16{}; p1 = f32x16{};
; #pragma unroll
;   for (int d0 = 0; d0 < 8; ++d0) { int cb = (d0 * 16 + hi * 8) * 2;
;     bf16x8 b0 = *reinterpret_cast<const bf16x8*>((const char*)Ks + KSWZ(r32, cb));
;     bf16x8 b1 = *reinterpret_cast<const bf16x8*>((const char*)Ks + KSWZ(32 + r32, cb));
;     p0 = __builtin_amdgcn_mfma_f32_32x32x16_bf16(b0, qr[d0], p0, 0, 0, 0);
;     p1 = __builtin_amdgcn_mfma_f32_32x32x16_bf16(b1, qr[d0], p1, 0, 0, 0); }
; }
.LBB0_518:
	s_cmp_lt_i32 s58, s97
	s_cselect_b64 s[4:5], -1, 0
	s_cmp_gt_i32 s58, s29
	s_cselect_b64 s[48:49], -1, 0
	s_or_b64 s[4:5], s[4:5], s[48:49]
	s_and_b64 vcc, exec, s[4:5]
	s_cbranch_vccnz .LBB0_526
	s_sub_i32 s4, s78, 64
	s_cmp_ge_u32 s4, s1
	ds_read_b128 v[64:67], v208 offset:32768
	ds_read_b128 v[68:71], v208 offset:40960
	ds_read_b128 v[168:171], v209 offset:32768
	ds_read_b128 v[172:175], v209 offset:40960
	ds_read_b128 v[176:179], v210 offset:32768
	ds_read_b128 v[180:183], v210 offset:40960
	ds_read_b128 v[184:187], v211 offset:32768
	ds_read_b128 v[188:191], v211 offset:40960
	s_waitcnt lgkmcnt(7)
	v_mfma_f32_32x32x16_bf16 v[80:95], v[64:67], v[96:99], 0
	s_waitcnt lgkmcnt(6)
	v_mfma_f32_32x32x16_bf16 v[64:79], v[68:71], v[96:99], 0
	ds_read_b128 v[192:195], v212 offset:32768
	ds_read_b128 v[196:199], v212 offset:40960
	s_waitcnt lgkmcnt(7)
	v_mfma_f32_32x32x16_bf16 v[80:95], v[168:171], v[100:103], v[80:95]
	s_waitcnt lgkmcnt(6)
	v_mfma_f32_32x32x16_bf16 v[64:79], v[172:175], v[100:103], v[64:79]
	ds_read_b128 v[168:171], v213 offset:32768
	ds_read_b128 v[172:175], v213 offset:40960
	s_waitcnt lgkmcnt(7)
	v_mfma_f32_32x32x16_bf16 v[80:95], v[176:179], v[104:107], v[80:95]
	s_waitcnt lgkmcnt(6)
	v_mfma_f32_32x32x16_bf16 v[64:79], v[180:183], v[104:107], v[64:79]
	ds_read_b128 v[176:179], v214 offset:32768
	ds_read_b128 v[180:183], v214 offset:40960
	s_waitcnt lgkmcnt(7)
	v_mfma_f32_32x32x16_bf16 v[80:95], v[184:187], v[108:111], v[80:95]
	s_waitcnt lgkmcnt(6)
	v_mfma_f32_32x32x16_bf16 v[64:79], v[188:191], v[108:111], v[64:79]
	ds_read_b128 v[184:187], v215 offset:32768
	ds_read_b128 v[188:191], v215 offset:40960
	s_waitcnt lgkmcnt(7)
	v_mfma_f32_32x32x16_bf16 v[80:95], v[192:195], v[112:115], v[80:95]
	s_waitcnt lgkmcnt(6)
	v_mfma_f32_32x32x16_bf16 v[64:79], v[196:199], v[112:115], v[64:79]
	s_waitcnt lgkmcnt(5)
	v_mfma_f32_32x32x16_bf16 v[80:95], v[168:171], v[116:119], v[80:95]
	s_waitcnt lgkmcnt(4)
	v_mfma_f32_32x32x16_bf16 v[64:79], v[172:175], v[116:119], v[64:79]
	s_waitcnt lgkmcnt(3)
	v_mfma_f32_32x32x16_bf16 v[80:95], v[176:179], v[120:123], v[80:95]
	s_waitcnt lgkmcnt(2)
	v_mfma_f32_32x32x16_bf16 v[64:79], v[180:183], v[120:123], v[64:79]
	s_waitcnt lgkmcnt(1)
	v_mfma_f32_32x32x16_bf16 v[80:95], v[184:187], v[124:127], v[80:95]
	s_waitcnt lgkmcnt(0)
	v_mfma_f32_32x32x16_bf16 v[64:79], v[188:191], v[124:127], v[64:79]
	s_cbranch_scc1 .Lbq_inf1
	ds_read2_b32 v[176:177], v205 offset1:1
	ds_read2_b32 v[178:179], v205 offset0:2 offset1:3
	ds_read2_b32 v[182:183], v205 offset0:8 offset1:9
	ds_read2_b32 v[180:181], v205 offset0:10 offset1:11
	ds_read2_b32 v[172:173], v205 offset0:16 offset1:17
	ds_read2_b32 v[174:175], v205 offset0:18 offset1:19
	ds_read2_b32 v[170:171], v205 offset0:24 offset1:25
	ds_read2_b32 v[168:169], v205 offset0:26 offset1:27
	ds_read2_b32 v[196:197], v205 offset0:32 offset1:33
	ds_read2_b32 v[198:199], v205 offset0:34 offset1:35
	ds_read2_b32 v[194:195], v205 offset0:40 offset1:41
	ds_read2_b32 v[190:191], v205 offset0:42 offset1:43
	s_waitcnt lgkmcnt(4)
	v_pk_add_f32 v[168:169], v[94:95], v[168:169]
	v_pk_add_f32 v[170:171], v[92:93], v[170:171]
	v_pk_add_f32 v[174:175], v[90:91], v[174:175]
	v_pk_add_f32 v[172:173], v[88:89], v[172:173]
	ds_read2_b32 v[88:89], v205 offset0:48 offset1:49
	ds_read2_b32 v[90:91], v205 offset0:50 offset1:51
	ds_read2_b32 v[92:93], v205 offset0:56 offset1:57
	ds_read2_b32 v[94:95], v205 offset0:58 offset1:59
	v_pk_add_f32 v[180:181], v[86:87], v[180:181]
	v_pk_add_f32 v[182:183], v[84:85], v[182:183]
	v_pk_add_f32 v[178:179], v[82:83], v[178:179]
	v_pk_add_f32 v[176:177], v[80:81], v[176:177]
	s_waitcnt lgkmcnt(0)
	v_pk_add_f32 v[184:185], v[78:79], v[94:95]
	v_pk_add_f32 v[186:187], v[76:77], v[92:93]
	v_pk_add_f32 v[188:189], v[74:75], v[90:91]
	v_pk_add_f32 v[192:193], v[72:73], v[88:89]
	v_pk_add_f32 v[190:191], v[70:71], v[190:191]
	v_pk_add_f32 v[194:195], v[68:69], v[194:195]
	v_pk_add_f32 v[198:199], v[66:67], v[198:199]
	v_pk_add_f32 v[196:197], v[64:65], v[196:197]

; __device__ __forceinline__ void partialSM(f32x16& p0, f32x16& p1, float& m_reg, float& mn, float& alpha) {
;     ...
;   float mnC = -mn * C;
; #pragma unroll
;   for (int r = 0; r < 16; ++r) p0[r] = fmaf(p0[r], C, mnC);
; #pragma unroll
;   for (int r = 0; r < 16; ++r) p1[r] = fmaf(p1[r], C, mnC);
; #pragma unroll
;   for (int r = 0; r < 16; ++r) p0[r] = __builtin_amdgcn_exp2f(p0[r]);
; }
; __device__ __forceinline__ void finishSM(f32x16& p0, f32x16& p1, float alpha, float& l_reg, bf16x8& pa0, bf16x8& pa1, bf16x8& pa2, bf16x8& pa3) {
; #pragma unroll
;   for (int r = 0; r < 16; ++r) p1[r] = __builtin_amdgcn_exp2f(p1[r]);
;   float ps = 0;
; #pragma unroll
;   for (int r = 0; r < 16; ++r) ps += p0[r];
; #pragma unroll
;   for (int r = 0; r < 16; ++r) ps += p1[r];
;   { auto rr = __builtin_amdgcn_permlane32_swap(__float_as_uint(ps), __float_as_uint(ps), false, false);
;     ps = __uint_as_float(rr[0]) + __uint_as_float(rr[1]); }
;   l_reg = l_reg * alpha + ps;
;     ...
;   PK4(p0, 0, pa0); PK4(p0, 8, pa1); PK4(p1, 0, pa2); PK4(p1, 8, pa3);
;     ...
; }
; __device__ __forceinline__ void qkt(f32x16& p0, f32x16& p1, const bf16* Ks, const bf16x8* qr, int r32, int hi) {
;   p0 = f32x16{}; p1 = f32x16{};
; #pragma unroll
;   for (int d0 = 0; d0 < 8; ++d0) { int cb = (d0 * 16 + hi * 8) * 2;
;     bf16x8 b0 = *reinterpret_cast<const bf16x8*>((const char*)Ks + KSWZ(r32, cb));
;     bf16x8 b1 = *reinterpret_cast<const bf16x8*>((const char*)Ks + KSWZ(32 + r32, cb));
;     p0 = __builtin_amdgcn_mfma_f32_32x32x16_bf16(b0, qr[d0], p0, 0, 0, 0);
;     p1 = __builtin_amdgcn_mfma_f32_32x32x16_bf16(b1, qr[d0], p1, 0, 0, 0); }
; }
; __device__ __forceinline__ int v_st(int k, int c) { const int kk = (k & ~0xC) | ((k & 4) << 1) | ((k & 8) >> 1); return ((kk >> 3) * 4 + (c >> 5)) * 512 + ((kk & 7) * 32 + (c & 31)) * 2; }
; __device__ __forceinline__ int v_rd_base(int lane) { return ((lane & 3) << 3) | (((lane >> 2) & 3) << 6) | (((lane >> 4) & 1) << 5) | (((lane >> 5) & 1) << 8); }
; template <int OFF> __device__ __forceinline__ s16x4 tr_read(int vb) {
;   s16x4 r; asm volatile("ds_read_b64_tr_b16 %0, %1 offset:%2" : "=&v"(r) : "v"(vb), "i"(OFF) : "memory"); return r;
; }
; template <int D0> __device__ __forceinline__ void pv_one(f32x16& od, int vb, bf16x8 pa0, bf16x8 pa1, bf16x8 pa2, bf16x8 pa3) {
.LBB0_525:
	v_cndmask_b32_e64 v201, v65, v201, s[4:5]
	v_mul_f32_e32 v65, 0xbe0293ee, v201
	v_fmamk_f32 v66, v176, 0x3e0293ee, v65
	v_fmamk_f32 v67, v177, 0x3e0293ee, v65
	v_exp_f32_e32 v66, v66
	v_fmamk_f32 v68, v178, 0x3e0293ee, v65
	v_exp_f32_e32 v67, v67
	v_fmamk_f32 v69, v179, 0x3e0293ee, v65
	v_exp_f32_e32 v68, v68
	v_fmamk_f32 v70, v182, 0x3e0293ee, v65
	v_fmamk_f32 v71, v183, 0x3e0293ee, v65
	v_fmamk_f32 v72, v180, 0x3e0293ee, v65
	v_fmamk_f32 v73, v181, 0x3e0293ee, v65
	v_fmamk_f32 v74, v172, 0x3e0293ee, v65
	v_fmamk_f32 v75, v173, 0x3e0293ee, v65
	v_fmamk_f32 v76, v174, 0x3e0293ee, v65
	v_fmamk_f32 v77, v175, 0x3e0293ee, v65
	v_fmamk_f32 v78, v170, 0x3e0293ee, v65
	v_fmamk_f32 v79, v171, 0x3e0293ee, v65
	v_fmamk_f32 v80, v168, 0x3e0293ee, v65
	v_fmamk_f32 v81, v169, 0x3e0293ee, v65
	v_fmamk_f32 v82, v196, 0x3e0293ee, v65
	v_fmamk_f32 v83, v197, 0x3e0293ee, v65
	v_fmamk_f32 v84, v198, 0x3e0293ee, v65
	v_fmamk_f32 v85, v199, 0x3e0293ee, v65
	v_fmamk_f32 v86, v194, 0x3e0293ee, v65
	v_fmamk_f32 v87, v195, 0x3e0293ee, v65
	v_fmamk_f32 v88, v190, 0x3e0293ee, v65
	v_fmamk_f32 v89, v191, 0x3e0293ee, v65
	v_fmamk_f32 v90, v192, 0x3e0293ee, v65
	v_fmamk_f32 v91, v193, 0x3e0293ee, v65
	v_fmamk_f32 v92, v188, 0x3e0293ee, v65
	v_fmamk_f32 v93, v189, 0x3e0293ee, v65
	v_fmamk_f32 v94, v186, 0x3e0293ee, v65
	v_fmamk_f32 v95, v187, 0x3e0293ee, v65
	v_fmamk_f32 v168, v184, 0x3e0293ee, v65
	v_fmac_f32_e32 v65, 0x3e0293ee, v185
	ds_read_b64_tr_b16 v[176:177], v202 offset:0
	ds_read_b64_tr_b16 v[178:179], v202 offset:0x800
	ds_read_b64_tr_b16 v[180:181], v202 offset:0x1000
	ds_read_b64_tr_b16 v[182:183], v202 offset:0x1800
	ds_read_b64_tr_b16 v[184:185], v202 offset:0x2000
	ds_read_b64_tr_b16 v[186:187], v202 offset:0x2800
	ds_read_b64_tr_b16 v[188:189], v202 offset:0x3000
	ds_read_b64_tr_b16 v[190:191], v202 offset:0x3800
	v_exp_f32_e32 v69, v69
	v_exp_f32_e32 v70, v70
	v_exp_f32_e32 v169, v65
	v_add_f32_e32 v65, 0, v66
	v_exp_f32_e32 v71, v71
	v_add_f32_e32 v65, v67, v65
	v_exp_f32_e32 v72, v72
	v_add_f32_e32 v65, v68, v65
	v_exp_f32_e32 v73, v73
	v_add_f32_e32 v65, v69, v65
	v_exp_f32_e32 v74, v74
	v_add_f32_e32 v65, v70, v65
	v_exp_f32_e32 v75, v75
	v_add_f32_e32 v65, v71, v65
	v_exp_f32_e32 v76, v76
	v_add_f32_e32 v65, v72, v65
	v_exp_f32_e32 v77, v77
	v_add_f32_e32 v65, v73, v65
	v_exp_f32_e32 v78, v78
	v_add_f32_e32 v65, v74, v65
	v_exp_f32_e32 v79, v79
	v_add_f32_e32 v65, v75, v65
	v_exp_f32_e32 v80, v80
	v_add_f32_e32 v65, v76, v65
	v_exp_f32_e32 v81, v81
	v_add_f32_e32 v65, v77, v65
	v_exp_f32_e32 v82, v82
	v_add_f32_e32 v65, v78, v65
	v_exp_f32_e32 v83, v83
	v_add_f32_e32 v65, v79, v65
	v_exp_f32_e32 v84, v84
	v_add_f32_e32 v65, v80, v65
	v_exp_f32_e32 v85, v85
	v_add_f32_e32 v65, v81, v65
	v_exp_f32_e32 v86, v86
	v_add_f32_e32 v65, v82, v65
	v_exp_f32_e32 v87, v87
	v_add_f32_e32 v65, v83, v65
	v_exp_f32_e32 v88, v88
	v_add_f32_e32 v65, v84, v65
	v_exp_f32_e32 v89, v89
	v_add_f32_e32 v65, v85, v65
	v_exp_f32_e32 v90, v90
	v_add_f32_e32 v65, v86, v65
	v_exp_f32_e32 v91, v91
	v_add_f32_e32 v65, v87, v65
	v_exp_f32_e32 v92, v92
	v_add_f32_e32 v65, v88, v65
	v_exp_f32_e32 v93, v93
	v_add_f32_e32 v65, v89, v65
	v_exp_f32_e32 v94, v94
	v_add_f32_e32 v65, v90, v65
	v_exp_f32_e32 v95, v95
	v_add_f32_e32 v65, v91, v65
	v_exp_f32_e32 v168, v168
	v_add_f32_e32 v65, v92, v65
	v_add_f32_e32 v65, v93, v65
	v_add_f32_e32 v65, v94, v65
	v_add_f32_e32 v65, v95, v65
	v_add_f32_e32 v65, v168, v65
	v_add_f32_e32 v65, v169, v65
	v_mov_b32_e32 v170, v65
	s_nop 1
	v_permlane32_swap_b32_e32 v65, v170
	v_add_f32_e32 v172, v65, v170
	v_fmac_f32_e32 v172, v216, v64
	v_cvt_pk_bf16_f32 v64, v66, v67
	v_cvt_pk_bf16_f32 v65, v68, v69
	v_cvt_pk_bf16_f32 v66, v70, v71
	v_cvt_pk_bf16_f32 v67, v72, v73
	v_cvt_pk_bf16_f32 v68, v74, v75
	v_cvt_pk_bf16_f32 v69, v76, v77
	v_cvt_pk_bf16_f32 v70, v78, v79
	v_cvt_pk_bf16_f32 v71, v80, v81
	v_cvt_pk_bf16_f32 v72, v82, v83
	v_cvt_pk_bf16_f32 v73, v84, v85
	v_cvt_pk_bf16_f32 v74, v86, v87
	v_cvt_pk_bf16_f32 v75, v88, v89
	v_cvt_pk_bf16_f32 v76, v90, v91
	v_cvt_pk_bf16_f32 v77, v92, v93
	v_cvt_pk_bf16_f32 v78, v94, v95
	v_cvt_pk_bf16_f32 v79, v168, v169
	s_nop 0
	v_permlane32_swap_b32_e32 v64, v66
	v_permlane32_swap_b32_e32 v65, v67
	v_permlane32_swap_b32_e32 v68, v70
	v_permlane32_swap_b32_e32 v69, v71
	v_permlane32_swap_b32_e32 v72, v74
	v_permlane32_swap_b32_e32 v73, v75
	v_permlane32_swap_b32_e32 v76, v78
	v_permlane32_swap_b32_e32 v77, v79
	s_waitcnt lgkmcnt(0)
	s_nop 0
	v_mfma_f32_32x32x16_bf16 v[0:15], v[64:67], v[176:179], v[0:15]
	ds_read_b64_tr_b16 v[80:81], v202 offset:0x200
	ds_read_b64_tr_b16 v[82:83], v202 offset:0xa00
	v_mfma_f32_32x32x16_bf16 v[0:15], v[68:71], v[180:183], v[0:15]
	ds_read_b64_tr_b16 v[84:85], v202 offset:0x1200
	ds_read_b64_tr_b16 v[86:87], v202 offset:0x1a00
	v_mfma_f32_32x32x16_bf16 v[0:15], v[72:75], v[184:187], v[0:15]
	ds_read_b64_tr_b16 v[88:89], v202 offset:0x2200
	ds_read_b64_tr_b16 v[90:91], v202 offset:0x2a00
	ds_read_b64_tr_b16 v[168:169], v202 offset:0x3200
	ds_read_b64_tr_b16 v[170:171], v202 offset:0x3a00
	s_waitcnt lgkmcnt(0)
	v_mfma_f32_32x32x16_bf16 v[0:15], v[76:79], v[188:191], v[0:15]
	v_mfma_f32_32x32x16_bf16 v[48:63], v[64:67], v[80:83], v[48:63]
	ds_read_b64_tr_b16 v[80:81], v202 offset:0x400
	ds_read_b64_tr_b16 v[82:83], v202 offset:0xc00
	v_mfma_f32_32x32x16_bf16 v[48:63], v[68:71], v[84:87], v[48:63]
	ds_read_b64_tr_b16 v[84:85], v202 offset:0x1400
	ds_read_b64_tr_b16 v[86:87], v202 offset:0x1c00
	v_mfma_f32_32x32x16_bf16 v[48:63], v[72:75], v[88:91], v[48:63]
	ds_read_b64_tr_b16 v[88:89], v202 offset:0x2400
	ds_read_b64_tr_b16 v[90:91], v202 offset:0x2c00
	ds_read_b64_tr_b16 v[92:93], v202 offset:0x3400
	ds_read_b64_tr_b16 v[94:95], v202 offset:0x3c00
	s_waitcnt lgkmcnt(0)
	v_mfma_f32_32x32x16_bf16 v[48:63], v[76:79], v[168:171], v[48:63]
	v_mfma_f32_32x32x16_bf16 v[32:47], v[64:67], v[80:83], v[32:47]
	ds_read_b64_tr_b16 v[80:81], v202 offset:0x600
	ds_read_b64_tr_b16 v[82:83], v202 offset:0xe00
	v_mfma_f32_32x32x16_bf16 v[32:47], v[68:71], v[84:87], v[32:47]
	ds_read_b64_tr_b16 v[84:85], v202 offset:0x1600
	ds_read_b64_tr_b16 v[86:87], v202 offset:0x1e00
	v_mfma_f32_32x32x16_bf16 v[32:47], v[72:75], v[88:91], v[32:47]
	ds_read_b64_tr_b16 v[88:89], v202 offset:0x2600
	ds_read_b64_tr_b16 v[90:91], v202 offset:0x2e00
	ds_read_b64_tr_b16 v[168:169], v202 offset:0x3600
	ds_read_b64_tr_b16 v[170:171], v202 offset:0x3e00
	s_waitcnt lgkmcnt(0)
	v_mfma_f32_32x32x16_bf16 v[32:47], v[76:79], v[92:95], v[32:47]
	v_mfma_f32_32x32x16_bf16 v[16:31], v[64:67], v[80:83], v[16:31]
	v_mov_b32_e32 v216, v172
	v_mfma_f32_32x32x16_bf16 v[16:31], v[68:71], v[84:87], v[16:31]
	v_mfma_f32_32x32x16_bf16 v[16:31], v[72:75], v[88:91], v[16:31]
	v_mfma_f32_32x32x16_bf16 v[16:31], v[76:79], v[168:171], v[16:31]

; __device__ __forceinline__ void qkt(f32x16& p0, f32x16& p1, const bf16* Ks, const bf16x8* qr, int r32, int hi) {
;   p0 = f32x16{}; p1 = f32x16{};
; #pragma unroll
;   for (int d0 = 0; d0 < 8; ++d0) { int cb = (d0 * 16 + hi * 8) * 2;
;     bf16x8 b0 = *reinterpret_cast<const bf16x8*>((const char*)Ks + KSWZ(r32, cb));
;     bf16x8 b1 = *reinterpret_cast<const bf16x8*>((const char*)Ks + KSWZ(32 + r32, cb));
;     p0 = __builtin_amdgcn_mfma_f32_32x32x16_bf16(b0, qr[d0], p0, 0, 0, 0);
;     p1 = __builtin_amdgcn_mfma_f32_32x32x16_bf16(b1, qr[d0], p1, 0, 0, 0); }
; }
.LBB0_528:
	s_add_i32 s4, s58, 1
	s_cmp_ge_i32 s4, s97
	s_cselect_b64 s[4:5], -1, 0
	s_cmp_lt_i32 s58, s29
	s_cselect_b64 s[48:49], -1, 0
	s_and_b64 s[4:5], s[4:5], s[48:49]
	s_andn2_b64 vcc, exec, s[4:5]
	s_cbranch_vccnz .LBB0_515
	s_cmp_ge_u32 s78, s1
	ds_read_b128 v[64:67], v208 offset:49152
	ds_read_b128 v[68:71], v208 offset:57344
	ds_read_b128 v[168:171], v209 offset:49152
	ds_read_b128 v[172:175], v209 offset:57344
	ds_read_b128 v[176:179], v210 offset:49152
	ds_read_b128 v[180:183], v210 offset:57344
	ds_read_b128 v[184:187], v211 offset:49152
	ds_read_b128 v[188:191], v211 offset:57344
	s_waitcnt lgkmcnt(7)
	v_mfma_f32_32x32x16_bf16 v[80:95], v[64:67], v[96:99], 0
	s_waitcnt lgkmcnt(6)
	v_mfma_f32_32x32x16_bf16 v[64:79], v[68:71], v[96:99], 0
	ds_read_b128 v[192:195], v212 offset:49152
	ds_read_b128 v[196:199], v212 offset:57344
	s_waitcnt lgkmcnt(7)
	v_mfma_f32_32x32x16_bf16 v[80:95], v[168:171], v[100:103], v[80:95]
	s_waitcnt lgkmcnt(6)
	v_mfma_f32_32x32x16_bf16 v[64:79], v[172:175], v[100:103], v[64:79]
	ds_read_b128 v[168:171], v213 offset:49152
	ds_read_b128 v[172:175], v213 offset:57344
	s_waitcnt lgkmcnt(7)
	v_mfma_f32_32x32x16_bf16 v[80:95], v[176:179], v[104:107], v[80:95]
	s_waitcnt lgkmcnt(6)
	v_mfma_f32_32x32x16_bf16 v[64:79], v[180:183], v[104:107], v[64:79]
	ds_read_b128 v[176:179], v214 offset:49152
	ds_read_b128 v[180:183], v214 offset:57344
	s_waitcnt lgkmcnt(7)
	v_mfma_f32_32x32x16_bf16 v[80:95], v[184:187], v[108:111], v[80:95]
	s_waitcnt lgkmcnt(6)
	v_mfma_f32_32x32x16_bf16 v[64:79], v[188:191], v[108:111], v[64:79]
	ds_read_b128 v[184:187], v215 offset:49152
	ds_read_b128 v[188:191], v215 offset:57344
	s_waitcnt lgkmcnt(7)
	v_mfma_f32_32x32x16_bf16 v[80:95], v[192:195], v[112:115], v[80:95]
	s_waitcnt lgkmcnt(6)
	v_mfma_f32_32x32x16_bf16 v[64:79], v[196:199], v[112:115], v[64:79]
	s_waitcnt lgkmcnt(5)
	v_mfma_f32_32x32x16_bf16 v[80:95], v[168:171], v[116:119], v[80:95]
	s_waitcnt lgkmcnt(4)
	v_mfma_f32_32x32x16_bf16 v[64:79], v[172:175], v[116:119], v[64:79]
	s_waitcnt lgkmcnt(3)
	v_mfma_f32_32x32x16_bf16 v[80:95], v[176:179], v[120:123], v[80:95]
	s_waitcnt lgkmcnt(2)
	v_mfma_f32_32x32x16_bf16 v[64:79], v[180:183], v[120:123], v[64:79]
	s_waitcnt lgkmcnt(1)
	v_mfma_f32_32x32x16_bf16 v[80:95], v[184:187], v[124:127], v[80:95]
	s_waitcnt lgkmcnt(0)
	v_mfma_f32_32x32x16_bf16 v[64:79], v[188:191], v[124:127], v[64:79]
	s_cbranch_scc1 .Lbq_inf2
	ds_read2_b32 v[176:177], v205 offset0:64 offset1:65
	ds_read2_b32 v[178:179], v205 offset0:66 offset1:67
	ds_read2_b32 v[182:183], v205 offset0:72 offset1:73
	ds_read2_b32 v[180:181], v205 offset0:74 offset1:75
	ds_read2_b32 v[172:173], v205 offset0:80 offset1:81
	ds_read2_b32 v[174:175], v205 offset0:82 offset1:83
	ds_read2_b32 v[170:171], v205 offset0:88 offset1:89
	ds_read2_b32 v[168:169], v205 offset0:90 offset1:91
	ds_read2_b32 v[196:197], v205 offset0:96 offset1:97
	ds_read2_b32 v[198:199], v205 offset0:98 offset1:99
	ds_read2_b32 v[194:195], v205 offset0:104 offset1:105
	ds_read2_b32 v[190:191], v205 offset0:106 offset1:107
	s_waitcnt lgkmcnt(4)
	v_pk_add_f32 v[168:169], v[94:95], v[168:169]
	v_pk_add_f32 v[170:171], v[92:93], v[170:171]
	v_pk_add_f32 v[174:175], v[90:91], v[174:175]
	v_pk_add_f32 v[172:173], v[88:89], v[172:173]
	ds_read2_b32 v[88:89], v205 offset0:112 offset1:113
	ds_read2_b32 v[90:91], v205 offset0:114 offset1:115
	ds_read2_b32 v[92:93], v205 offset0:120 offset1:121
	ds_read2_b32 v[94:95], v205 offset0:122 offset1:123
	v_pk_add_f32 v[180:181], v[86:87], v[180:181]
	v_pk_add_f32 v[182:183], v[84:85], v[182:183]
	v_pk_add_f32 v[178:179], v[82:83], v[178:179]
	v_pk_add_f32 v[176:177], v[80:81], v[176:177]
	s_waitcnt lgkmcnt(0)
	v_pk_add_f32 v[184:185], v[78:79], v[94:95]
	v_pk_add_f32 v[186:187], v[76:77], v[92:93]
	v_pk_add_f32 v[188:189], v[74:75], v[90:91]
	v_pk_add_f32 v[192:193], v[72:73], v[88:89]
	v_pk_add_f32 v[190:191], v[70:71], v[190:191]
	v_pk_add_f32 v[194:195], v[68:69], v[194:195]
	v_pk_add_f32 v[198:199], v[66:67], v[198:199]
	v_pk_add_f32 v[196:197], v[64:65], v[196:197]

.Lbq_inf1:
	v_mov_b32_e32 v168, 0xff800000
	v_mov_b32_e32 v169, 0xff800000
	v_mov_b32_e32 v170, 0xff800000
	v_mov_b32_e32 v171, 0xff800000
	v_mov_b32_e32 v172, 0xff800000
	v_mov_b32_e32 v173, 0xff800000
	v_mov_b32_e32 v174, 0xff800000
	v_mov_b32_e32 v175, 0xff800000
	v_mov_b32_e32 v176, 0xff800000
	v_mov_b32_e32 v177, 0xff800000
	v_mov_b32_e32 v178, 0xff800000
	v_mov_b32_e32 v179, 0xff800000
	v_mov_b32_e32 v180, 0xff800000
	v_mov_b32_e32 v181, 0xff800000
	v_mov_b32_e32 v182, 0xff800000
	v_mov_b32_e32 v183, 0xff800000
	v_mov_b32_e32 v184, 0xff800000
	v_mov_b32_e32 v185, 0xff800000
	v_mov_b32_e32 v186, 0xff800000
	v_mov_b32_e32 v187, 0xff800000
	v_mov_b32_e32 v188, 0xff800000
	v_mov_b32_e32 v189, 0xff800000
	v_mov_b32_e32 v190, 0xff800000
	v_mov_b32_e32 v191, 0xff800000
	v_mov_b32_e32 v192, 0xff800000
	v_mov_b32_e32 v193, 0xff800000
	v_mov_b32_e32 v194, 0xff800000
	v_mov_b32_e32 v195, 0xff800000
	v_mov_b32_e32 v196, 0xff800000
	v_mov_b32_e32 v197, 0xff800000
	v_mov_b32_e32 v198, 0xff800000
	v_mov_b32_e32 v199, 0xff800000
	s_branch .LBB0_521
